# XCD-local seams use one non-returning arrival on a per-XCC monotonic counter plus polling of that counter (no per-XCC leader / generation word)
# baseline (speedup 1.0000x reference)
; #define LAS __attribute__((address_space(3)))
; __global__ void __launch_bounds__(NWAVES * 64, 2) trunk_fwd(Args args) {
;     extern __shared__ __attribute__((aligned(16))) unsigned char lds[];
;     cg::grid_group grid = cg::this_grid();
;     LAS unsigned char* L = (LAS unsigned char*)lds;
;     if (threadIdx.x == 0) { ((volatile LAS unsigned*)(L + XB_ST_OFF))[0] = 0u; ((volatile LAS unsigned*)(L + XB_ST_OFF))[1] = 0u; }
;     __syncthreads();
;     if (blockIdx.x == 0) for (int i = threadIdx.x; i < XCD_BAR_WORDS; i += NWAVES * 64) ((unsigned*)args.ws)[i] = 0u;
_Z9trunk_fwd4Args:
	s_add_u32 s8, s0, 0xe0
	v_writelane_b32 v255, s2, 0
	v_writelane_b32 v255, 0, 44
	v_writelane_b32 v255, 1, 42
	s_load_dwordx4 s[80:83], s[0:1], 0xd0
	s_load_dwordx2 s[2:3], s[0:1], 0xe0
	s_load_dword s76, s[0:1], 0xe8
	v_and_b32_e32 v206, 0x3ff, v0
	s_waitcnt lgkmcnt(0)
	v_writelane_b32 v255, s2, 1
	s_nop 1
	v_writelane_b32 v255, s3, 2
	v_writelane_b32 v255, s0, 3
	s_addc_u32 s9, s1, 0
	s_nop 0
	v_writelane_b32 v255, s1, 4
	v_cmp_eq_u32_e64 s[0:1], 0, v206
	s_nop 1
	v_writelane_b32 v255, s0, 5
	s_nop 1
	v_writelane_b32 v255, s1, 6
	s_and_saveexec_b64 s[4:5], s[0:1]
	s_cbranch_execz .LBB0_2
	s_add_i32 s1, 0, 0x23fc0
	v_mov_b32_e32 v1, 0
	v_mov_b32_e32 v2, s1
	s_add_i32 s1, 0, 0x23fc4
	ds_write_b32 v2, v1
	v_mov_b32_e32 v2, s1
	ds_write_b32 v2, v1

; __device__ __forceinline__ unsigned xb_ld(unsigned* p)              { return __hip_atomic_load(p, __ATOMIC_RELAXED, __HIP_MEMORY_SCOPE_AGENT); }
; __device__ __forceinline__ unsigned xb_add(unsigned* p, unsigned v) { return __hip_atomic_fetch_add(p, v, __ATOMIC_RELAXED, __HIP_MEMORY_SCOPE_AGENT); }
; #define XB_SPIN(cond, bar) do { unsigned _sp = 0; while (cond) { __builtin_amdgcn_s_sleep(1); \
;     if ((++_sp & 255u) == 0u) { if (xb_ld(&(bar)[XB_TMO])) break; if (_sp > XB_SPIN_CAP) { atomicAdd(&(bar)[XB_TMO], 1u); break; } } } } while (0)
; __device__ __forceinline__ void xcd_barrier(const XcdBarrier& b) {
;     asm volatile("s_waitcnt vmcnt(0)" ::: "memory");
;     __syncthreads();
;     if (threadIdx.x == 0) {
;         unsigned* bar = b.bar;
;         __builtin_amdgcn_s_waitcnt(0);
;         unsigned nloc = b.st[0], nx = b.st[1];
;         if (nloc == 0u) { xcd_barrier_complete(bar, b.x, nloc, nx); b.st[0] = nloc; b.st[1] = nx; }
;         const unsigned old = xb_add(&bar[XB_XSUB(b.x)], 1u);
;         const unsigned gen = old / nloc;
;         if (old + 1u == (gen + 1u) * nloc) {
;             __builtin_amdgcn_fence(__ATOMIC_RELEASE, "agent");
;             asm volatile("s_waitcnt vmcnt(0)" ::: "memory");
;             const unsigned og = xb_add(&bar[XB_TOP], 1u);
;             const unsigned tg = og / nx;
;             if (og + 1u == (tg + 1u) * nx) xb_add(&bar[XB_TOPGEN], 1u);
;             else XB_SPIN(xb_ld(&bar[XB_TOPGEN]) == tg, bar);
;             __builtin_amdgcn_fence(__ATOMIC_ACQUIRE, "agent");
;             xb_add(&bar[XB_XGEN(b.x)], 1u);
;             asm volatile("s_waitcnt vmcnt(0)" ::: "memory");
;         } else {
;             XB_SPIN(xb_ld(&bar[XB_XGEN(b.x)]) == gen, bar);
;             __builtin_amdgcn_fence(__ATOMIC_ACQUIRE, "agent");
;             asm volatile("s_waitcnt vmcnt(0)" ::: "memory");
;         }
;     }
;     __syncthreads();
; }
.LBB0_636:
	v_readlane_b32 s8, v255, 9
	s_sub_u32 s8, s8, 3
	s_cmp_lt_u32 s8, 26
	s_cbranch_scc0 .Llb_normal
	v_readlane_b32 s8, v255, 42
	s_cmp_eq_u32 s8, 0
	s_cbranch_scc0 .Llb_normal
	s_lshl_b32 s8, s0, 8
	s_add_u32 s6, s18, s8
	s_addc_u32 s7, s19, 0
	v_readlane_b32 s8, v255, 44
	s_add_i32 s8, s8, 1
	v_writelane_b32 v255, s8, 44
	v_mul_lo_u32 v4, v3, s8
	v_mov_b32_e32 v5, 1
	v_mov_b32_e32 v6, 0x1480
	global_atomic_add v6, v5, s[6:7]
	s_mov_b32 s9, 0
.Llb_spin:
	global_load_dword v7, v6, s[6:7] sc1
	s_waitcnt vmcnt(0)
	v_sub_u32_e32 v8, v7, v4
	v_cmp_gt_i32_e32 vcc, 0, v8
	s_cbranch_vccz .Llb_done
	s_sleep 1
	s_add_i32 s9, s9, 1
	s_cmp_lt_u32 s9, 0x4000
	s_cbranch_scc1 .Llb_spin
.Llb_done:
	buffer_inv sc1
	s_waitcnt vmcnt(0)
	s_branch .LBB0_169
